# FRes epilogue: bj0 block also issues the bj1 block's four loads (one exposed latency per row section); on top of LR2/RGG bias hoists and 8-step scan combine
# baseline (speedup 1.0000x reference)
.LBB0_104:
	s_or_b64 exec, exec, s[60:61]
	s_and_saveexec_b64 s[60:61], s[58:59]
	s_cbranch_execz .LBB0_106
	global_load_dwordx4 v[168:171], v[144:145], off
	global_load_dwordx4 v[184:187], v[166:167], off
	global_load_dwordx4 v[194:197], v[144:145], off offset:64
	global_load_dwordx4 v[198:201], v[166:167], off offset:64
	global_load_dwordx4 v[202:205], v[144:145], off offset:512
	global_load_dwordx4 v[206:209], v[166:167], off offset:512
	global_load_dwordx4 v[210:213], v[144:145], off offset:576
	global_load_dwordx4 v[214:217], v[166:167], off offset:576
	s_waitcnt vmcnt(6)
	v_pk_fma_f32 v[170:171], v[126:127], v[186:187], v[170:171]
	v_pk_fma_f32 v[168:169], v[124:125], v[184:185], v[168:169]
	global_store_dwordx4 v[140:141], v[168:171], off
	s_waitcnt vmcnt(5)
	v_pk_fma_f32 v[196:197], v[122:123], v[200:201], v[196:197]
	v_pk_fma_f32 v[194:195], v[120:121], v[198:199], v[194:195]
	global_store_dwordx4 v[140:141], v[194:197], off offset:64

.LBB0_148:
	global_load_dwordx4 v[170:173], v[138:139], off
	global_load_dwordx4 v[186:189], v[168:169], off
	global_load_dwordx4 v[194:197], v[138:139], off offset:64
	global_load_dwordx4 v[198:201], v[168:169], off offset:64
	global_load_dwordx4 v[202:205], v[138:139], off offset:512
	global_load_dwordx4 v[206:209], v[168:169], off offset:512
	global_load_dwordx4 v[210:213], v[138:139], off offset:576
	global_load_dwordx4 v[214:217], v[168:169], off offset:576
	s_waitcnt vmcnt(6)
	v_pk_fma_f32 v[172:173], v[126:127], v[188:189], v[172:173]
	v_pk_fma_f32 v[170:171], v[124:125], v[186:187], v[170:171]
	global_store_dwordx4 v[138:139], v[170:173], off
	s_waitcnt vmcnt(5)
	v_pk_fma_f32 v[196:197], v[122:123], v[200:201], v[196:197]
	v_pk_fma_f32 v[194:195], v[120:121], v[198:199], v[194:195]
	global_store_dwordx4 v[138:139], v[194:197], off offset:64

.LBB0_165:
	s_waitcnt vmcnt(4)
	v_pk_fma_f32 v[204:205], v[118:119], v[208:209], v[204:205]
	v_pk_fma_f32 v[202:203], v[116:117], v[206:207], v[202:203]
	global_store_dwordx4 v[122:123], v[202:205], off
	s_waitcnt vmcnt(3)
	v_pk_fma_f32 v[212:213], v[114:115], v[216:217], v[212:213]
	v_pk_fma_f32 v[210:211], v[112:113], v[214:215], v[210:211]
	global_store_dwordx4 v[122:123], v[210:213], off offset:64

.LBB0_224:
	global_load_dwordx4 v[144:147], v[116:117], off
	global_load_dwordx4 v[170:173], v[142:143], off
	global_load_dwordx4 v[194:197], v[116:117], off offset:64
	global_load_dwordx4 v[198:201], v[142:143], off offset:64
	global_load_dwordx4 v[202:205], v[116:117], off offset:512
	global_load_dwordx4 v[206:209], v[142:143], off offset:512
	global_load_dwordx4 v[210:213], v[116:117], off offset:576
	global_load_dwordx4 v[214:217], v[142:143], off offset:576
	s_waitcnt vmcnt(6)
	v_pk_fma_f32 v[146:147], v[110:111], v[172:173], v[146:147]
	v_pk_fma_f32 v[144:145], v[108:109], v[170:171], v[144:145]
	global_store_dwordx4 v[112:113], v[144:147], off
	s_waitcnt vmcnt(5)
	v_pk_fma_f32 v[196:197], v[106:107], v[200:201], v[196:197]
	v_pk_fma_f32 v[194:195], v[104:105], v[198:199], v[194:195]
	global_store_dwordx4 v[112:113], v[194:197], off offset:64

.LBB0_266:
	global_load_dwordx4 v[146:149], v[142:143], off
	global_load_dwordx4 v[170:173], v[144:145], off
	global_load_dwordx4 v[194:197], v[142:143], off offset:64
	global_load_dwordx4 v[198:201], v[144:145], off offset:64
	global_load_dwordx4 v[202:205], v[142:143], off offset:512
	global_load_dwordx4 v[206:209], v[144:145], off offset:512
	global_load_dwordx4 v[210:213], v[142:143], off offset:576
	global_load_dwordx4 v[214:217], v[144:145], off offset:576
	s_waitcnt vmcnt(6)
	v_pk_fma_f32 v[148:149], v[110:111], v[172:173], v[148:149]
	v_pk_fma_f32 v[146:147], v[108:109], v[170:171], v[146:147]
	global_store_dwordx4 v[142:143], v[146:149], off
	s_waitcnt vmcnt(5)
	v_pk_fma_f32 v[196:197], v[106:107], v[200:201], v[196:197]
	v_pk_fma_f32 v[194:195], v[104:105], v[198:199], v[194:195]
	global_store_dwordx4 v[142:143], v[194:197], off offset:64

.LBB0_283:
	s_waitcnt vmcnt(4)
	v_pk_fma_f32 v[204:205], v[102:103], v[208:209], v[204:205]
	v_pk_fma_f32 v[202:203], v[100:101], v[206:207], v[202:203]
	global_store_dwordx4 v[104:105], v[202:205], off
	s_waitcnt vmcnt(3)
	v_pk_fma_f32 v[212:213], v[98:99], v[216:217], v[212:213]
	v_pk_fma_f32 v[210:211], v[96:97], v[214:215], v[210:211]
	global_store_dwordx4 v[104:105], v[210:213], off offset:64

.LBB0_342:
	global_load_dwordx4 v[112:115], v[100:101], off
	global_load_dwordx4 v[116:119], v[110:111], off
	global_load_dwordx4 v[194:197], v[100:101], off offset:64
	global_load_dwordx4 v[198:201], v[110:111], off offset:64
	global_load_dwordx4 v[202:205], v[100:101], off offset:512
	global_load_dwordx4 v[206:209], v[110:111], off offset:512
	global_load_dwordx4 v[210:213], v[100:101], off offset:576
	global_load_dwordx4 v[214:217], v[110:111], off offset:576
	s_waitcnt vmcnt(6)
	v_pk_fma_f32 v[114:115], v[94:95], v[118:119], v[114:115]
	v_pk_fma_f32 v[112:113], v[92:93], v[116:117], v[112:113]
	global_store_dwordx4 v[96:97], v[112:115], off
	s_waitcnt vmcnt(5)
	v_pk_fma_f32 v[196:197], v[90:91], v[200:201], v[196:197]
	v_pk_fma_f32 v[194:195], v[88:89], v[198:199], v[194:195]
	global_store_dwordx4 v[96:97], v[194:197], off offset:64

.LBB0_384:
	global_load_dwordx4 v[114:117], v[110:111], off
	global_load_dwordx4 v[124:127], v[112:113], off
	global_load_dwordx4 v[194:197], v[110:111], off offset:64
	global_load_dwordx4 v[198:201], v[112:113], off offset:64
	global_load_dwordx4 v[202:205], v[110:111], off offset:512
	global_load_dwordx4 v[206:209], v[112:113], off offset:512
	global_load_dwordx4 v[210:213], v[110:111], off offset:576
	global_load_dwordx4 v[214:217], v[112:113], off offset:576
	s_waitcnt vmcnt(6)
	v_pk_fma_f32 v[116:117], v[94:95], v[126:127], v[116:117]
	v_pk_fma_f32 v[114:115], v[92:93], v[124:125], v[114:115]
	global_store_dwordx4 v[110:111], v[114:117], off
	s_waitcnt vmcnt(5)
	v_pk_fma_f32 v[196:197], v[90:91], v[200:201], v[196:197]
	v_pk_fma_f32 v[194:195], v[88:89], v[198:199], v[194:195]
	global_store_dwordx4 v[110:111], v[194:197], off offset:64

.LBB0_401:
	s_waitcnt vmcnt(4)
	v_pk_fma_f32 v[204:205], v[86:87], v[208:209], v[204:205]
	v_pk_fma_f32 v[202:203], v[84:85], v[206:207], v[202:203]
	global_store_dwordx4 v[88:89], v[202:205], off
	s_waitcnt vmcnt(3)
	v_pk_fma_f32 v[212:213], v[82:83], v[216:217], v[212:213]
	v_pk_fma_f32 v[210:211], v[80:81], v[214:215], v[210:211]
	global_store_dwordx4 v[88:89], v[210:213], off offset:64

.LBB0_460:
	global_load_dwordx4 v[96:99], v[84:85], off
	global_load_dwordx4 v[100:103], v[94:95], off
	global_load_dwordx4 v[194:197], v[84:85], off offset:64
	global_load_dwordx4 v[198:201], v[94:95], off offset:64
	global_load_dwordx4 v[202:205], v[84:85], off offset:512
	global_load_dwordx4 v[206:209], v[94:95], off offset:512
	global_load_dwordx4 v[210:213], v[84:85], off offset:576
	global_load_dwordx4 v[214:217], v[94:95], off offset:576
	s_waitcnt vmcnt(6)
	v_pk_fma_f32 v[98:99], v[78:79], v[102:103], v[98:99]
	v_pk_fma_f32 v[96:97], v[76:77], v[100:101], v[96:97]
	global_store_dwordx4 v[80:81], v[96:99], off
	s_waitcnt vmcnt(5)
	v_pk_fma_f32 v[196:197], v[74:75], v[200:201], v[196:197]
	v_pk_fma_f32 v[194:195], v[72:73], v[198:199], v[194:195]
	global_store_dwordx4 v[80:81], v[194:197], off offset:64

.LBB0_502:
	global_load_dwordx4 v[98:101], v[94:95], off
	global_load_dwordx4 v[104:107], v[96:97], off
	global_load_dwordx4 v[194:197], v[94:95], off offset:64
	global_load_dwordx4 v[198:201], v[96:97], off offset:64
	global_load_dwordx4 v[202:205], v[94:95], off offset:512
	global_load_dwordx4 v[206:209], v[96:97], off offset:512
	global_load_dwordx4 v[210:213], v[94:95], off offset:576
	global_load_dwordx4 v[214:217], v[96:97], off offset:576
	s_waitcnt vmcnt(6)
	v_pk_fma_f32 v[100:101], v[78:79], v[106:107], v[100:101]
	v_pk_fma_f32 v[98:99], v[76:77], v[104:105], v[98:99]
	global_store_dwordx4 v[94:95], v[98:101], off
	s_waitcnt vmcnt(5)
	v_pk_fma_f32 v[196:197], v[74:75], v[200:201], v[196:197]
	v_pk_fma_f32 v[194:195], v[72:73], v[198:199], v[194:195]
	global_store_dwordx4 v[94:95], v[194:197], off offset:64

.LBB0_519:
	s_waitcnt vmcnt(4)
	v_pk_fma_f32 v[204:205], v[70:71], v[208:209], v[204:205]
	v_pk_fma_f32 v[202:203], v[68:69], v[206:207], v[202:203]
	global_store_dwordx4 v[72:73], v[202:205], off
	s_waitcnt vmcnt(3)
	v_pk_fma_f32 v[212:213], v[66:67], v[216:217], v[212:213]
	v_pk_fma_f32 v[210:211], v[64:65], v[214:215], v[210:211]
	global_store_dwordx4 v[72:73], v[210:213], off offset:64

.LBB0_578:
	global_load_dwordx4 v[80:83], v[68:69], off
	global_load_dwordx4 v[84:87], v[78:79], off
	global_load_dwordx4 v[194:197], v[68:69], off offset:64
	global_load_dwordx4 v[198:201], v[78:79], off offset:64
	global_load_dwordx4 v[202:205], v[68:69], off offset:512
	global_load_dwordx4 v[206:209], v[78:79], off offset:512
	global_load_dwordx4 v[210:213], v[68:69], off offset:576
	global_load_dwordx4 v[214:217], v[78:79], off offset:576
	s_waitcnt vmcnt(6)
	v_pk_fma_f32 v[82:83], v[62:63], v[86:87], v[82:83]
	v_pk_fma_f32 v[80:81], v[60:61], v[84:85], v[80:81]
	global_store_dwordx4 v[64:65], v[80:83], off
	s_waitcnt vmcnt(5)
	v_pk_fma_f32 v[196:197], v[58:59], v[200:201], v[196:197]
	v_pk_fma_f32 v[194:195], v[56:57], v[198:199], v[194:195]
	global_store_dwordx4 v[64:65], v[194:197], off offset:64

.LBB0_620:
	global_load_dwordx4 v[82:85], v[78:79], off
	global_load_dwordx4 v[88:91], v[80:81], off
	global_load_dwordx4 v[194:197], v[78:79], off offset:64
	global_load_dwordx4 v[198:201], v[80:81], off offset:64
	global_load_dwordx4 v[202:205], v[78:79], off offset:512
	global_load_dwordx4 v[206:209], v[80:81], off offset:512
	global_load_dwordx4 v[210:213], v[78:79], off offset:576
	global_load_dwordx4 v[214:217], v[80:81], off offset:576
	s_waitcnt vmcnt(6)
	v_pk_fma_f32 v[84:85], v[62:63], v[90:91], v[84:85]
	v_pk_fma_f32 v[82:83], v[60:61], v[88:89], v[82:83]
	global_store_dwordx4 v[78:79], v[82:85], off
	s_waitcnt vmcnt(5)
	v_pk_fma_f32 v[196:197], v[58:59], v[200:201], v[196:197]
	v_pk_fma_f32 v[194:195], v[56:57], v[198:199], v[194:195]
	global_store_dwordx4 v[78:79], v[194:197], off offset:64

.LBB0_637:
	s_waitcnt vmcnt(4)
	v_pk_fma_f32 v[204:205], v[54:55], v[208:209], v[204:205]
	v_pk_fma_f32 v[202:203], v[52:53], v[206:207], v[202:203]
	global_store_dwordx4 v[56:57], v[202:205], off
	s_waitcnt vmcnt(3)
	v_pk_fma_f32 v[212:213], v[50:51], v[216:217], v[212:213]
	v_pk_fma_f32 v[210:211], v[48:49], v[214:215], v[210:211]
	global_store_dwordx4 v[56:57], v[210:213], off offset:64

.LBB0_696:
	global_load_dwordx4 v[64:67], v[52:53], off
	global_load_dwordx4 v[68:71], v[62:63], off
	global_load_dwordx4 v[194:197], v[52:53], off offset:64
	global_load_dwordx4 v[198:201], v[62:63], off offset:64
	global_load_dwordx4 v[202:205], v[52:53], off offset:512
	global_load_dwordx4 v[206:209], v[62:63], off offset:512
	global_load_dwordx4 v[210:213], v[52:53], off offset:576
	global_load_dwordx4 v[214:217], v[62:63], off offset:576
	s_waitcnt vmcnt(6)
	v_pk_fma_f32 v[66:67], v[46:47], v[70:71], v[66:67]
	v_pk_fma_f32 v[64:65], v[44:45], v[68:69], v[64:65]
	global_store_dwordx4 v[48:49], v[64:67], off
	s_waitcnt vmcnt(5)
	v_pk_fma_f32 v[196:197], v[42:43], v[200:201], v[196:197]
	v_pk_fma_f32 v[194:195], v[40:41], v[198:199], v[194:195]
	global_store_dwordx4 v[48:49], v[194:197], off offset:64

.LBB0_738:
	global_load_dwordx4 v[66:69], v[62:63], off
	global_load_dwordx4 v[72:75], v[64:65], off
	global_load_dwordx4 v[194:197], v[62:63], off offset:64
	global_load_dwordx4 v[198:201], v[64:65], off offset:64
	global_load_dwordx4 v[202:205], v[62:63], off offset:512
	global_load_dwordx4 v[206:209], v[64:65], off offset:512
	global_load_dwordx4 v[210:213], v[62:63], off offset:576
	global_load_dwordx4 v[214:217], v[64:65], off offset:576
	s_waitcnt vmcnt(6)
	v_pk_fma_f32 v[68:69], v[46:47], v[74:75], v[68:69]
	v_pk_fma_f32 v[66:67], v[44:45], v[72:73], v[66:67]
	global_store_dwordx4 v[62:63], v[66:69], off
	s_waitcnt vmcnt(5)
	v_pk_fma_f32 v[196:197], v[42:43], v[200:201], v[196:197]
	v_pk_fma_f32 v[194:195], v[40:41], v[198:199], v[194:195]
	global_store_dwordx4 v[62:63], v[194:197], off offset:64

.LBB0_755:
	s_waitcnt vmcnt(4)
	v_pk_fma_f32 v[204:205], v[38:39], v[208:209], v[204:205]
	v_pk_fma_f32 v[202:203], v[36:37], v[206:207], v[202:203]
	global_store_dwordx4 v[40:41], v[202:205], off
	s_waitcnt vmcnt(3)
	v_pk_fma_f32 v[212:213], v[34:35], v[216:217], v[212:213]
	v_pk_fma_f32 v[210:211], v[32:33], v[214:215], v[210:211]
	global_store_dwordx4 v[40:41], v[210:213], off offset:64

.LBB0_814:
	global_load_dwordx4 v[48:51], v[36:37], off
	global_load_dwordx4 v[52:55], v[46:47], off
	global_load_dwordx4 v[194:197], v[36:37], off offset:64
	global_load_dwordx4 v[198:201], v[46:47], off offset:64
	global_load_dwordx4 v[202:205], v[36:37], off offset:512
	global_load_dwordx4 v[206:209], v[46:47], off offset:512
	global_load_dwordx4 v[210:213], v[36:37], off offset:576
	global_load_dwordx4 v[214:217], v[46:47], off offset:576
	s_waitcnt vmcnt(6)
	v_pk_fma_f32 v[50:51], v[30:31], v[54:55], v[50:51]
	v_pk_fma_f32 v[48:49], v[28:29], v[52:53], v[48:49]
	global_store_dwordx4 v[32:33], v[48:51], off
	s_waitcnt vmcnt(5)
	v_pk_fma_f32 v[196:197], v[26:27], v[200:201], v[196:197]
	v_pk_fma_f32 v[194:195], v[24:25], v[198:199], v[194:195]
	global_store_dwordx4 v[32:33], v[194:197], off offset:64

.LBB0_856:
	global_load_dwordx4 v[50:53], v[46:47], off
	global_load_dwordx4 v[56:59], v[48:49], off
	global_load_dwordx4 v[194:197], v[46:47], off offset:64
	global_load_dwordx4 v[198:201], v[48:49], off offset:64
	global_load_dwordx4 v[202:205], v[46:47], off offset:512
	global_load_dwordx4 v[206:209], v[48:49], off offset:512
	global_load_dwordx4 v[210:213], v[46:47], off offset:576
	global_load_dwordx4 v[214:217], v[48:49], off offset:576
	s_waitcnt vmcnt(6)
	v_pk_fma_f32 v[52:53], v[30:31], v[58:59], v[52:53]
	v_pk_fma_f32 v[50:51], v[28:29], v[56:57], v[50:51]
	global_store_dwordx4 v[46:47], v[50:53], off
	s_waitcnt vmcnt(5)
	v_pk_fma_f32 v[196:197], v[26:27], v[200:201], v[196:197]
	v_pk_fma_f32 v[194:195], v[24:25], v[198:199], v[194:195]
	global_store_dwordx4 v[46:47], v[194:197], off offset:64

.LBB0_873:
	s_waitcnt vmcnt(4)
	v_pk_fma_f32 v[204:205], v[22:23], v[208:209], v[204:205]
	v_pk_fma_f32 v[202:203], v[20:21], v[206:207], v[202:203]
	global_store_dwordx4 v[24:25], v[202:205], off
	s_waitcnt vmcnt(3)
	v_pk_fma_f32 v[212:213], v[18:19], v[216:217], v[212:213]
	v_pk_fma_f32 v[210:211], v[16:17], v[214:215], v[210:211]
	global_store_dwordx4 v[24:25], v[210:213], off offset:64

.LBB0_932:
	global_load_dwordx4 v[32:35], v[20:21], off
	global_load_dwordx4 v[36:39], v[30:31], off
	global_load_dwordx4 v[194:197], v[20:21], off offset:64
	global_load_dwordx4 v[198:201], v[30:31], off offset:64
	global_load_dwordx4 v[202:205], v[20:21], off offset:512
	global_load_dwordx4 v[206:209], v[30:31], off offset:512
	global_load_dwordx4 v[210:213], v[20:21], off offset:576
	global_load_dwordx4 v[214:217], v[30:31], off offset:576
	s_waitcnt vmcnt(6)
	v_pk_fma_f32 v[34:35], v[14:15], v[38:39], v[34:35]
	v_pk_fma_f32 v[32:33], v[12:13], v[36:37], v[32:33]
	global_store_dwordx4 v[16:17], v[32:35], off
	s_waitcnt vmcnt(5)
	v_pk_fma_f32 v[196:197], v[10:11], v[200:201], v[196:197]
	v_pk_fma_f32 v[194:195], v[8:9], v[198:199], v[194:195]
	global_store_dwordx4 v[16:17], v[194:197], off offset:64

.LBB0_974:
	global_load_dwordx4 v[34:37], v[30:31], off
	global_load_dwordx4 v[40:43], v[32:33], off
	global_load_dwordx4 v[194:197], v[30:31], off offset:64
	global_load_dwordx4 v[198:201], v[32:33], off offset:64
	global_load_dwordx4 v[202:205], v[30:31], off offset:512
	global_load_dwordx4 v[206:209], v[32:33], off offset:512
	global_load_dwordx4 v[210:213], v[30:31], off offset:576
	global_load_dwordx4 v[214:217], v[32:33], off offset:576
	s_waitcnt vmcnt(6)
	v_pk_fma_f32 v[36:37], v[14:15], v[42:43], v[36:37]
	v_pk_fma_f32 v[34:35], v[12:13], v[40:41], v[34:35]
	global_store_dwordx4 v[30:31], v[34:37], off
	s_waitcnt vmcnt(5)
	v_pk_fma_f32 v[196:197], v[10:11], v[200:201], v[196:197]
	v_pk_fma_f32 v[194:195], v[8:9], v[198:199], v[194:195]
	global_store_dwordx4 v[30:31], v[194:197], off offset:64

.LBB0_991:
	s_waitcnt vmcnt(4)
	v_pk_fma_f32 v[204:205], v[6:7], v[208:209], v[204:205]
	v_pk_fma_f32 v[202:203], v[4:5], v[206:207], v[202:203]
	global_store_dwordx4 v[8:9], v[202:205], off
	s_waitcnt vmcnt(3)
	v_pk_fma_f32 v[212:213], v[2:3], v[216:217], v[212:213]
	v_pk_fma_f32 v[210:211], v[0:1], v[214:215], v[210:211]
	global_store_dwordx4 v[8:9], v[210:213], off offset:64
